# v8 + P7 K-loop load segments rewritten: LDS-DMA with SGPR base + 32-bit lane offset (no per-DMA VALU address add), ds_reads first, pointer arithmetic after the DMAs, loop-invariant LDS read bases in s
# speedup vs baseline: 1.1120x; 1.1120x over previous
; __device__ __forceinline__ int lane_id() { int l; asm volatile("v_mbcnt_lo_u32_b32 %0, -1, 0\n\tv_mbcnt_hi_u32_b32 %0, -1, %0" : "=v"(l)); return l; }
; #define PG8_STAGE(bufoff, gbase, voff) do { _Pragma("unroll") for (int _i = 0; _i < 2; ++_i) \
;         __builtin_amdgcn_global_load_lds((const unsigned*)((const char*)(gbase) + (voff)[_i]), (LAS unsigned*)(lds + (bufoff) + ldsw + _i * 8192), 16, 0, 0); } while (0)
; #define PG8_WAIT_V(n) asm volatile("s_waitcnt vmcnt(" #n ")" ::: "memory")
; #define PG8_BAR __builtin_amdgcn_s_barrier()
; template <class Epi, bool ALIGN_EPI = true, bool FP8 = false>
; __device__ __forceinline__ void gemm_phase(LAS unsigned char* lds, const Gemm g, const StaticOrder& S, const Epi& E, const int wid) {
;     const int lane = lane_id(), tid = wid * 64 + lane, wr = wid >> 2, wc = wid & 3, fr = lane & 15, fq = lane >> 4;
;     const int K = g.K;
;     unsigned voffA[2], voffB[2];
; #pragma unroll
;     for (int i = 0; i < 2; ++i) { int R, C; stage_rc(tid * 16 + i * 8192, R, C); const int Rb = Epi::PERM ? ((R & ~31) + perm32(R & 31)) : R;
;         const unsigned rpb = FP8 ? (unsigned)K : 2u * (unsigned)K;
;         voffA[i] = (unsigned)R * rpb + (unsigned)C * 2u; voffB[i] = (unsigned)Rb * rpb + (unsigned)C * 2u; }
;     const size_t kstep = (size_t)(BK * 2);
;     const size_t hstep = (size_t)HALF * K * (FP8 ? 1 : 2);
;     const size_t tstep = 2 * hstep;
;     const unsigned ldsw = (unsigned)wid * 1024u;
;     const int aoff = lds_byte(wr * 64 + fr, fq * 8);
;     const int boff = lds_byte(wc * 32 + fr, fq * 8);
;     ...
;     const char* cA = PG8_UA(cur); const char* cB = PG8_UB(cur);
;     PG8_STAGE(PG8_SB(0, 0), cB, voffB); PG8_STAGE(PG8_SB(0, 1), cB + hstep, voffB); PG8_STAGE(PG8_SA(0, 0), cA, voffA); PG8_STAGE(PG8_SA(0, 1), cA + hstep, voffA);
;     if (wr == 1) PG8_BAR;
;     PG8_WAIT_V(2); PG8_BAR;
;     PG8_STAGE(PG8_SB(1, 0), cB + kstep, voffB); PG8_STAGE(PG8_SA(1, 0), cA + kstep, voffA); PG8_STAGE(PG8_SB(1, 1), cB + hstep + kstep, voffB);
;     PG8_WAIT_V(6); PG8_BAR;
.LBB0_2447:
	s_lshl_b32 s10, s50, 5
	s_and_b32 s10, s10, 0x60
	s_lshl_b32 s16, s3, 13
	s_lshr_b32 s17, s10, 3
	s_and_b64 s[4:5], s[4:5], exec
	s_cselect_b32 s54, 0, 32
	s_cmpk_lt_u32 s96, 0x100
	s_mov_b64 s[14:15], 0x80
	s_cselect_b64 s[12:13], -1, 0
	v_lshl_add_u64 v[6:7], v[6:7], 0, s[14:15]
	s_add_i32 m0, s25, 0x18000
	s_ashr_i32 s50, s2, 31
	s_ashr_i32 s51, s33, 31
	s_waitcnt vmcnt(2)
	s_barrier
	global_load_lds_dwordx4 v[6:7], off
	v_lshl_add_u64 v[4:5], v[4:5], 0, s[14:15]
	s_add_i32 m0, s25, 0x1a000
	s_add_i32 s53, s25, 0x8000
	s_add_i32 s55, s25, 0xa000
	global_load_lds_dwordx4 v[4:5], off
	v_lshl_add_u64 v[2:3], v[2:3], 0, s[14:15]
	s_mov_b32 m0, s53
	s_add_u32 s4, s30, 0x80080
	global_load_lds_dwordx4 v[2:3], off
	v_lshl_add_u64 v[0:1], v[0:1], 0, s[14:15]
	s_mov_b32 m0, s55
	s_addc_u32 s5, s31, 0
	global_load_lds_dwordx4 v[0:1], off
	v_lshl_add_u64 v[0:1], s[4:5], 0, v[132:133]
	s_add_i32 m0, s25, 0x1c000
	v_and_b32_e32 v2, 48, v8
	global_load_lds_dwordx4 v[0:1], off
	v_lshl_add_u64 v[0:1], s[4:5], 0, v[128:129]
	s_add_i32 m0, s25, 0x1e000
	s_mov_b32 s11, 0
	global_load_lds_dwordx4 v[0:1], off
	v_and_b32_e32 v0, 15, v8
	v_ashrrev_i32_e32 v1, 1, v8
	v_lshl_or_b32 v146, s3, 6, v0
	v_and_b32_e32 v136, -8, v1
	v_ashrrev_i32_e32 v1, 6, v8
	v_lshl_or_b32 v0, v0, 6, v2
	v_lshlrev_b32_e32 v2, 2, v8
	v_lshl_add_u32 v3, v1, 10, s16
	v_and_b32_e32 v2, 32, v2
	v_add_lshl_u32 v1, v1, s17, 10
	v_bitop3_b32 v3, v0, v3, v2 bitop3:0xde
	v_bitop3_b32 v147, v0, v1, v2 bitop3:0xde
	v_lshlrev_b32_e32 v0, 15, v12
	v_and_b32_e32 v0, 0xffff0000, v0
	v_lshl_add_u32 v0, v13, 12, v0
	v_and_b32_e32 v1, 1, v12
	v_lshl_or_b32 v0, v1, 6, v0
	v_lshl_add_u32 v138, v14, 1, v0
	v_lshlrev_b32_e32 v0, 15, v9
	v_and_b32_e32 v0, 0xffff0000, v0
	s_waitcnt vmcnt(6)
	v_lshl_add_u32 v0, v10, 12, v0
	v_and_b32_e32 v1, 1, v9
	v_lshl_or_b32 v0, v1, 6, v0
	s_add_i32 s65, 0, 0x10000
	s_add_i32 s66, 0, 0x14000
	v_ashrrev_i32_e32 v137, 31, v136
	v_mov_b32_e32 v139, v133
	v_lshl_add_u32 v140, v11, 1, v0
	v_mov_b32_e32 v141, v133
	v_mov_b64_e32 v[142:143], 0x1658
	s_movk_i32 s64, 0x2cc
	v_add_u32_e32 v148, s65, v147
	v_add_u32_e32 v149, s66, v147
	v_add_u32_e32 v224, 0x18000, v147
	v_add_u32_e32 v225, 0x1c000, v147
	v_add_u32_e32 v150, 0, v3
	s_movk_i32 s67, 0x1600
	s_mov_b32 s68, 0xc3e00000
	s_mov_b32 s69, 0x2c000
	s_mov_b32 s70, 0x42000
	s_mov_b32 s71, 0xb0000
	s_mov_b32 s72, 0xc6000
	s_mov_b32 s73, 0xdc000
	v_mov_b32_e32 v151, 0x43e00000
	s_mov_b32 s74, s11
	s_barrier
	s_waitcnt vmcnt(0)
	s_branch .LBB0_2450

; #define PG8_STAGE(bufoff, gbase, voff) do { _Pragma("unroll") for (int _i = 0; _i < 2; ++_i) \
;         __builtin_amdgcn_global_load_lds((const unsigned*)((const char*)(gbase) + (voff)[_i]), (LAS unsigned*)(lds + (bufoff) + ldsw + _i * 8192), 16, 0, 0); } while (0)
; #define PG8_LDA(dst, b, h) do { _Pragma("unroll") for (int m = 0; m < 4; ++m) _Pragma("unroll") for (int k = 0; k < 2; ++k) dst[m][k] = *(const LAS bf16x8*)(lds + PG8_SA(b, h) + aoff + m * 2048 + k * KOFF); } while (0)
; #define PG8_LDB(dst, b, h) do { _Pragma("unroll") for (int n = 0; n < 2; ++n) _Pragma("unroll") for (int k = 0; k < 2; ++k) dst[n][k] = *(const LAS bf16x8*)(lds + PG8_SB(b, h) + boff + n * 2048 + k * KOFF); } while (0)
; #define PG8_WAIT_V(n) asm volatile("s_waitcnt vmcnt(" #n ")" ::: "memory")
; #define PG8_WAIT_L(n) asm volatile("s_waitcnt lgkmcnt(" #n ")" ::: "memory")
; #define PG8_BAR __builtin_amdgcn_s_barrier()
; #define PG8_SCHED __builtin_amdgcn_sched_barrier(0)
; template <class Epi, bool ALIGN_EPI = true, bool FP8 = false>
; __device__ __forceinline__ void gemm_phase(LAS unsigned char* lds, const Gemm g, const StaticOrder& S, const Epi& E, const int wid) {
;     ...
;             const char* a1 = cA + (size_t)(t + 1) * kstep;
;             const char* a2 = last ? nA : cA + (size_t)(t + 2) * kstep; const char* b2 = last ? nB : cB + (size_t)(t + 2) * kstep;
;             const char* a3 = a2 + kstep; const char* b3 = b2 + kstep;
;             PG8_LDB(B0, 0, 0); PG8_LDB(B1, 0, 1); PG8_SCHED; PG8_LDA(At, 0, 0); PG8_STAGE(PG8_SA(1, 1), a1 + hstep, voffA);
;             PG8_WAIT_V(8); PG8_WAIT_L(0); PG8_BAR; PG8_MMA(0, 0, At, B0); PG8_MMA(0, 1, At, B1); PG8_BAR; PG8_SCHED;
;             PG8_LDA(At, 0, 1); PG8_STAGE(PG8_SB(0, 0), b2, voffB); PG8_STAGE(PG8_SB(0, 1), b2 + hstep, voffB); PG8_STAGE(PG8_SA(0, 0), a2, voffA);
;             PG8_WAIT_V(8); PG8_WAIT_L(0); PG8_BAR; PG8_MMA(1, 0, At, B0); PG8_MMA(1, 1, At, B1); PG8_BAR; PG8_SCHED;
.LBB0_2452:
	ds_read_b128 v[152:155], v148
	ds_read_b128 v[156:159], v148 offset:1024
	ds_read_b128 v[160:163], v148 offset:2048
	ds_read_b128 v[164:167], v148 offset:3072
	ds_read_b128 v[168:171], v149
	ds_read_b128 v[172:175], v149 offset:1024
	ds_read_b128 v[176:179], v149 offset:2048
	ds_read_b128 v[180:183], v149 offset:3072
	ds_read_b128 v[184:187], v150
	ds_read_b128 v[188:191], v150 offset:1024
	ds_read_b128 v[192:195], v150 offset:2048
	ds_read_b128 v[196:199], v150 offset:3072
	ds_read_b128 v[200:203], v150 offset:4096
	ds_read_b128 v[204:207], v150 offset:5120
	ds_read_b128 v[208:211], v150 offset:6144
	ds_read_b128 v[212:215], v150 offset:7168
	s_add_i32 m0, s38, 0xc000
	s_nop 0
	global_load_lds_dwordx4 v138, s[28:29]
	s_add_i32 m0, s38, 0xe000
	s_nop 0
	global_load_lds_dwordx4 v140, s[28:29]
	s_add_i32 s76, s30, 2
	s_add_u32 s31, s28, 0xfff80080
	s_addc_u32 s34, s29, -1
	s_cmp_eq_u32 s43, s30
	s_cselect_b32 s30, s42, s52
	s_cselect_b32 s35, s3, s34
	s_cselect_b32 s34, s17, s31
	s_cselect_b32 s31, s19, s75
	s_add_u32 s78, s30, 0x80000
	s_addc_u32 s79, s31, 0
	s_add_u32 s100, s34, 0x80000
	s_addc_u32 s101, s35, 0
	s_setprio 1
	s_waitcnt vmcnt(8) lgkmcnt(0)
	s_barrier
	v_mfma_f32_16x16x32_bf16 v[124:127], v[152:155], v[184:187], v[124:127]
	v_mfma_f32_16x16x32_bf16 v[116:119], v[160:163], v[184:187], v[116:119]
	v_mfma_f32_16x16x32_bf16 v[108:111], v[152:155], v[192:195], v[108:111]
	v_mfma_f32_16x16x32_bf16 v[100:103], v[160:163], v[192:195], v[100:103]
	v_mfma_f32_16x16x32_bf16 v[92:95], v[152:155], v[200:203], v[92:95]
	v_mfma_f32_16x16x32_bf16 v[84:87], v[160:163], v[200:203], v[84:87]
	v_mfma_f32_16x16x32_bf16 v[76:79], v[152:155], v[208:211], v[76:79]
	v_mfma_f32_16x16x32_bf16 v[68:71], v[160:163], v[208:211], v[68:71]
	v_mfma_f32_16x16x32_bf16 v[124:127], v[156:159], v[188:191], v[124:127]
	v_mfma_f32_16x16x32_bf16 v[116:119], v[164:167], v[188:191], v[116:119]
	v_mfma_f32_16x16x32_bf16 v[108:111], v[156:159], v[196:199], v[108:111]
	v_mfma_f32_16x16x32_bf16 v[100:103], v[164:167], v[196:199], v[100:103]
	v_mfma_f32_16x16x32_bf16 v[92:95], v[156:159], v[204:207], v[92:95]
	v_mfma_f32_16x16x32_bf16 v[84:87], v[164:167], v[204:207], v[84:87]
	v_mfma_f32_16x16x32_bf16 v[76:79], v[156:159], v[212:215], v[76:79]
	v_mfma_f32_16x16x32_bf16 v[68:71], v[164:167], v[212:215], v[68:71]
	v_mfma_f32_16x16x32_bf16 v[120:123], v[168:171], v[184:187], v[120:123]
	v_mfma_f32_16x16x32_bf16 v[112:115], v[176:179], v[184:187], v[112:115]
	v_mfma_f32_16x16x32_bf16 v[104:107], v[168:171], v[192:195], v[104:107]
	v_mfma_f32_16x16x32_bf16 v[96:99], v[176:179], v[192:195], v[96:99]
	v_mfma_f32_16x16x32_bf16 v[88:91], v[168:171], v[200:203], v[88:91]
	v_mfma_f32_16x16x32_bf16 v[80:83], v[176:179], v[200:203], v[80:83]
	v_mfma_f32_16x16x32_bf16 v[72:75], v[168:171], v[208:211], v[72:75]
	v_mfma_f32_16x16x32_bf16 v[64:67], v[176:179], v[208:211], v[64:67]
	v_mfma_f32_16x16x32_bf16 v[120:123], v[172:175], v[188:191], v[120:123]
	v_mfma_f32_16x16x32_bf16 v[112:115], v[180:183], v[188:191], v[112:115]
	v_mfma_f32_16x16x32_bf16 v[104:107], v[172:175], v[196:199], v[104:107]
	v_mfma_f32_16x16x32_bf16 v[96:99], v[180:183], v[196:199], v[96:99]
	v_mfma_f32_16x16x32_bf16 v[88:91], v[172:175], v[204:207], v[88:91]
	v_mfma_f32_16x16x32_bf16 v[80:83], v[180:183], v[204:207], v[80:83]
	v_mfma_f32_16x16x32_bf16 v[72:75], v[172:175], v[212:215], v[72:75]
	v_mfma_f32_16x16x32_bf16 v[64:67], v[180:183], v[212:215], v[64:67]
	s_barrier
	s_setprio 0
	ds_read_b128 v[184:187], v150 offset:16384
	ds_read_b128 v[188:191], v150 offset:17408
	ds_read_b128 v[192:195], v150 offset:18432
	ds_read_b128 v[196:199], v150 offset:19456
	ds_read_b128 v[200:203], v150 offset:20480
	ds_read_b128 v[204:207], v150 offset:21504
	ds_read_b128 v[208:211], v150 offset:22528
	ds_read_b128 v[212:215], v150 offset:23552
	s_add_i32 m0, s38, 0x10000
	s_nop 0
	global_load_lds_dwordx4 v132, s[30:31]
	s_add_i32 m0, s38, 0x12000
	s_nop 0
	global_load_lds_dwordx4 v128, s[30:31]
	s_add_i32 m0, s38, 0x14000
	s_nop 0
	global_load_lds_dwordx4 v132, s[78:79]
	s_add_i32 m0, s38, 0x16000
	s_nop 0
	global_load_lds_dwordx4 v128, s[78:79]
	s_mov_b32 m0, s38
	s_nop 0
	global_load_lds_dwordx4 v134, s[34:35]
	s_add_i32 m0, s38, 0x2000
	s_nop 0
	global_load_lds_dwordx4 v130, s[34:35]
	s_setprio 1
	s_waitcnt vmcnt(8) lgkmcnt(0)
	s_barrier
	v_mfma_f32_16x16x32_bf16 v[60:63], v[152:155], v[184:187], v[60:63]
	v_mfma_f32_16x16x32_bf16 v[52:55], v[160:163], v[184:187], v[52:55]
	v_mfma_f32_16x16x32_bf16 v[44:47], v[152:155], v[192:195], v[44:47]
	v_mfma_f32_16x16x32_bf16 v[36:39], v[160:163], v[192:195], v[36:39]
	v_mfma_f32_16x16x32_bf16 v[28:31], v[152:155], v[200:203], v[28:31]
	v_mfma_f32_16x16x32_bf16 v[20:23], v[160:163], v[200:203], v[20:23]
	v_mfma_f32_16x16x32_bf16 v[12:15], v[152:155], v[208:211], v[12:15]
	v_mfma_f32_16x16x32_bf16 v[4:7], v[160:163], v[208:211], v[4:7]
	v_mfma_f32_16x16x32_bf16 v[60:63], v[156:159], v[188:191], v[60:63]
	v_mfma_f32_16x16x32_bf16 v[52:55], v[164:167], v[188:191], v[52:55]
	v_mfma_f32_16x16x32_bf16 v[44:47], v[156:159], v[196:199], v[44:47]
	v_mfma_f32_16x16x32_bf16 v[36:39], v[164:167], v[196:199], v[36:39]
	v_mfma_f32_16x16x32_bf16 v[28:31], v[156:159], v[204:207], v[28:31]
	v_mfma_f32_16x16x32_bf16 v[20:23], v[164:167], v[204:207], v[20:23]
	v_mfma_f32_16x16x32_bf16 v[12:15], v[156:159], v[212:215], v[12:15]
	v_mfma_f32_16x16x32_bf16 v[4:7], v[164:167], v[212:215], v[4:7]
	v_mfma_f32_16x16x32_bf16 v[56:59], v[168:171], v[184:187], v[56:59]
	v_mfma_f32_16x16x32_bf16 v[48:51], v[176:179], v[184:187], v[48:51]
	v_mfma_f32_16x16x32_bf16 v[40:43], v[168:171], v[192:195], v[40:43]
	v_mfma_f32_16x16x32_bf16 v[32:35], v[176:179], v[192:195], v[32:35]
	v_mfma_f32_16x16x32_bf16 v[24:27], v[168:171], v[200:203], v[24:27]
	v_mfma_f32_16x16x32_bf16 v[16:19], v[176:179], v[200:203], v[16:19]
	v_mfma_f32_16x16x32_bf16 v[8:11], v[168:171], v[208:211], v[8:11]
	v_mfma_f32_16x16x32_bf16 v[0:3], v[176:179], v[208:211], v[0:3]
	v_mfma_f32_16x16x32_bf16 v[56:59], v[172:175], v[188:191], v[56:59]
	v_mfma_f32_16x16x32_bf16 v[48:51], v[180:183], v[188:191], v[48:51]
	v_mfma_f32_16x16x32_bf16 v[40:43], v[172:175], v[196:199], v[40:43]
	v_mfma_f32_16x16x32_bf16 v[32:35], v[180:183], v[196:199], v[32:35]
	v_mfma_f32_16x16x32_bf16 v[24:27], v[172:175], v[204:207], v[24:27]
	v_mfma_f32_16x16x32_bf16 v[16:19], v[180:183], v[204:207], v[16:19]
	v_mfma_f32_16x16x32_bf16 v[8:11], v[172:175], v[212:215], v[8:11]
	v_mfma_f32_16x16x32_bf16 v[0:3], v[180:183], v[212:215], v[0:3]
	s_barrier
; #define PG8_STAGE(bufoff, gbase, voff) do { _Pragma("unroll") for (int _i = 0; _i < 2; ++_i) \
;         __builtin_amdgcn_global_load_lds((const unsigned*)((const char*)(gbase) + (voff)[_i]), (LAS unsigned*)(lds + (bufoff) + ldsw + _i * 8192), 16, 0, 0); } while (0)
; #define PG8_LDA(dst, b, h) do { _Pragma("unroll") for (int m = 0; m < 4; ++m) _Pragma("unroll") for (int k = 0; k < 2; ++k) dst[m][k] = *(const LAS bf16x8*)(lds + PG8_SA(b, h) + aoff + m * 2048 + k * KOFF); } while (0)
; #define PG8_LDB(dst, b, h) do { _Pragma("unroll") for (int n = 0; n < 2; ++n) _Pragma("unroll") for (int k = 0; k < 2; ++k) dst[n][k] = *(const LAS bf16x8*)(lds + PG8_SB(b, h) + boff + n * 2048 + k * KOFF); } while (0)
; #define PG8_WAIT_V(n) asm volatile("s_waitcnt vmcnt(" #n ")" ::: "memory")
; #define PG8_WAIT_L(n) asm volatile("s_waitcnt lgkmcnt(" #n ")" ::: "memory")
; #define PG8_BAR __builtin_amdgcn_s_barrier()
; #define PG8_SCHED __builtin_amdgcn_sched_barrier(0)
; template <class Epi, bool ALIGN_EPI = true, bool FP8 = false>
; __device__ __forceinline__ void gemm_phase(LAS unsigned char* lds, const Gemm g, const StaticOrder& S, const Epi& E, const int wid) {
;     ...
;             PG8_LDB(B0, 1, 0); PG8_LDB(B1, 1, 1); PG8_SCHED; PG8_LDA(At, 1, 0); PG8_STAGE(PG8_SA(0, 1), a2 + hstep, voffA);
;             PG8_WAIT_V(8); PG8_WAIT_L(0); PG8_BAR; PG8_MMA(0, 0, At, B0); PG8_MMA(0, 1, At, B1); PG8_BAR; PG8_SCHED;
;             PG8_LDA(At, 1, 1); PG8_STAGE(PG8_SB(1, 0), b3, voffB); PG8_STAGE(PG8_SB(1, 1), b3 + hstep, voffB); PG8_STAGE(PG8_SA(1, 0), a3, voffA);
;             PG8_WAIT_V(8); PG8_WAIT_L(0); PG8_BAR; PG8_MMA(1, 0, At, B0); PG8_MMA(1, 1, At, B1); PG8_BAR; PG8_SCHED;
;         }
	s_setprio 0
	ds_read_b128 v[152:155], v224
	ds_read_b128 v[156:159], v224 offset:1024
	ds_read_b128 v[160:163], v224 offset:2048
	ds_read_b128 v[164:167], v224 offset:3072
	ds_read_b128 v[168:171], v225
	ds_read_b128 v[172:175], v225 offset:1024
	ds_read_b128 v[176:179], v225 offset:2048
	ds_read_b128 v[180:183], v225 offset:3072
	ds_read_b128 v[184:187], v150 offset:32768
	ds_read_b128 v[188:191], v150 offset:33792
	ds_read_b128 v[192:195], v150 offset:34816
	ds_read_b128 v[196:199], v150 offset:35840
	ds_read_b128 v[200:203], v150 offset:36864
	ds_read_b128 v[204:207], v150 offset:37888
	ds_read_b128 v[208:211], v150 offset:38912
	ds_read_b128 v[212:215], v150 offset:39936
	s_add_i32 m0, s38, 0x4000
	s_nop 0
	global_load_lds_dwordx4 v134, s[100:101]
	s_add_i32 m0, s38, 0x6000
	s_nop 0
	global_load_lds_dwordx4 v130, s[100:101]
	s_add_u32 s30, s30, 0x80
	s_addc_u32 s31, s31, 0
	s_add_u32 s78, s78, 0x80
	s_addc_u32 s79, s79, 0
	s_add_u32 s34, s34, 0x80
	s_addc_u32 s35, s35, 0
	s_setprio 1
	s_waitcnt vmcnt(8) lgkmcnt(0)
	s_barrier
	v_mfma_f32_16x16x32_bf16 v[124:127], v[152:155], v[184:187], v[124:127]
	v_mfma_f32_16x16x32_bf16 v[116:119], v[160:163], v[184:187], v[116:119]
	v_mfma_f32_16x16x32_bf16 v[108:111], v[152:155], v[192:195], v[108:111]
	v_mfma_f32_16x16x32_bf16 v[100:103], v[160:163], v[192:195], v[100:103]
	v_mfma_f32_16x16x32_bf16 v[92:95], v[152:155], v[200:203], v[92:95]
	v_mfma_f32_16x16x32_bf16 v[84:87], v[160:163], v[200:203], v[84:87]
	v_mfma_f32_16x16x32_bf16 v[76:79], v[152:155], v[208:211], v[76:79]
	v_mfma_f32_16x16x32_bf16 v[68:71], v[160:163], v[208:211], v[68:71]
	v_mfma_f32_16x16x32_bf16 v[124:127], v[156:159], v[188:191], v[124:127]
	v_mfma_f32_16x16x32_bf16 v[116:119], v[164:167], v[188:191], v[116:119]
	v_mfma_f32_16x16x32_bf16 v[108:111], v[156:159], v[196:199], v[108:111]
	v_mfma_f32_16x16x32_bf16 v[100:103], v[164:167], v[196:199], v[100:103]
	v_mfma_f32_16x16x32_bf16 v[92:95], v[156:159], v[204:207], v[92:95]
	v_mfma_f32_16x16x32_bf16 v[84:87], v[164:167], v[204:207], v[84:87]
	v_mfma_f32_16x16x32_bf16 v[76:79], v[156:159], v[212:215], v[76:79]
	v_mfma_f32_16x16x32_bf16 v[68:71], v[164:167], v[212:215], v[68:71]
	v_mfma_f32_16x16x32_bf16 v[120:123], v[168:171], v[184:187], v[120:123]
	v_mfma_f32_16x16x32_bf16 v[112:115], v[176:179], v[184:187], v[112:115]
	v_mfma_f32_16x16x32_bf16 v[104:107], v[168:171], v[192:195], v[104:107]
	v_mfma_f32_16x16x32_bf16 v[96:99], v[176:179], v[192:195], v[96:99]
	v_mfma_f32_16x16x32_bf16 v[88:91], v[168:171], v[200:203], v[88:91]
	v_mfma_f32_16x16x32_bf16 v[80:83], v[176:179], v[200:203], v[80:83]
	v_mfma_f32_16x16x32_bf16 v[72:75], v[168:171], v[208:211], v[72:75]
	v_mfma_f32_16x16x32_bf16 v[64:67], v[176:179], v[208:211], v[64:67]
	v_mfma_f32_16x16x32_bf16 v[120:123], v[172:175], v[188:191], v[120:123]
	v_mfma_f32_16x16x32_bf16 v[112:115], v[180:183], v[188:191], v[112:115]
	v_mfma_f32_16x16x32_bf16 v[104:107], v[172:175], v[196:199], v[104:107]
	v_mfma_f32_16x16x32_bf16 v[96:99], v[180:183], v[196:199], v[96:99]
	v_mfma_f32_16x16x32_bf16 v[88:91], v[172:175], v[204:207], v[88:91]
	v_mfma_f32_16x16x32_bf16 v[80:83], v[180:183], v[204:207], v[80:83]
	v_mfma_f32_16x16x32_bf16 v[72:75], v[172:175], v[212:215], v[72:75]
	v_mfma_f32_16x16x32_bf16 v[64:67], v[180:183], v[212:215], v[64:67]
	s_barrier
	s_setprio 0
	ds_read_b128 v[184:187], v150 offset:49152
	ds_read_b128 v[188:191], v150 offset:50176
	ds_read_b128 v[192:195], v150 offset:51200
	ds_read_b128 v[196:199], v150 offset:52224
	ds_read_b128 v[200:203], v150 offset:53248
	ds_read_b128 v[204:207], v150 offset:54272
	ds_read_b128 v[208:211], v150 offset:55296
	ds_read_b128 v[212:215], v150 offset:56320
	s_add_i32 m0, s38, 0x18000
	s_nop 0
	global_load_lds_dwordx4 v132, s[30:31]
	s_add_i32 m0, s38, 0x1a000
	s_nop 0
	global_load_lds_dwordx4 v128, s[30:31]
	s_add_i32 m0, s38, 0x1c000
	s_nop 0
	global_load_lds_dwordx4 v132, s[78:79]
	s_add_i32 m0, s38, 0x1e000
	s_nop 0
	global_load_lds_dwordx4 v128, s[78:79]
	s_add_i32 m0, s38, 0x8000
	s_nop 0
	global_load_lds_dwordx4 v134, s[34:35]
	s_add_i32 m0, s38, 0xa000
	s_nop 0
	global_load_lds_dwordx4 v130, s[34:35]
	s_setprio 1
	s_waitcnt vmcnt(8) lgkmcnt(0)
	s_barrier
	v_mfma_f32_16x16x32_bf16 v[60:63], v[152:155], v[184:187], v[60:63]
	v_mfma_f32_16x16x32_bf16 v[52:55], v[160:163], v[184:187], v[52:55]
	v_mfma_f32_16x16x32_bf16 v[44:47], v[152:155], v[192:195], v[44:47]
	v_mfma_f32_16x16x32_bf16 v[36:39], v[160:163], v[192:195], v[36:39]
	v_mfma_f32_16x16x32_bf16 v[28:31], v[152:155], v[200:203], v[28:31]
	v_mfma_f32_16x16x32_bf16 v[20:23], v[160:163], v[200:203], v[20:23]
	v_mfma_f32_16x16x32_bf16 v[12:15], v[152:155], v[208:211], v[12:15]
	v_mfma_f32_16x16x32_bf16 v[4:7], v[160:163], v[208:211], v[4:7]
	v_mfma_f32_16x16x32_bf16 v[60:63], v[156:159], v[188:191], v[60:63]
	v_mfma_f32_16x16x32_bf16 v[52:55], v[164:167], v[188:191], v[52:55]
	v_mfma_f32_16x16x32_bf16 v[44:47], v[156:159], v[196:199], v[44:47]
	v_mfma_f32_16x16x32_bf16 v[36:39], v[164:167], v[196:199], v[36:39]
	v_mfma_f32_16x16x32_bf16 v[28:31], v[156:159], v[204:207], v[28:31]
	v_mfma_f32_16x16x32_bf16 v[20:23], v[164:167], v[204:207], v[20:23]
	v_mfma_f32_16x16x32_bf16 v[12:15], v[156:159], v[212:215], v[12:15]
	v_mfma_f32_16x16x32_bf16 v[4:7], v[164:167], v[212:215], v[4:7]
	v_mfma_f32_16x16x32_bf16 v[56:59], v[168:171], v[184:187], v[56:59]
	v_mfma_f32_16x16x32_bf16 v[48:51], v[176:179], v[184:187], v[48:51]
	v_mfma_f32_16x16x32_bf16 v[40:43], v[168:171], v[192:195], v[40:43]
	v_mfma_f32_16x16x32_bf16 v[32:35], v[176:179], v[192:195], v[32:35]
	v_mfma_f32_16x16x32_bf16 v[24:27], v[168:171], v[200:203], v[24:27]
	v_mfma_f32_16x16x32_bf16 v[16:19], v[176:179], v[200:203], v[16:19]
	v_mfma_f32_16x16x32_bf16 v[8:11], v[168:171], v[208:211], v[8:11]
	v_mfma_f32_16x16x32_bf16 v[0:3], v[176:179], v[208:211], v[0:3]
	v_mfma_f32_16x16x32_bf16 v[56:59], v[172:175], v[188:191], v[56:59]
	v_mfma_f32_16x16x32_bf16 v[48:51], v[180:183], v[188:191], v[48:51]
	v_mfma_f32_16x16x32_bf16 v[40:43], v[172:175], v[196:199], v[40:43]
	v_mfma_f32_16x16x32_bf16 v[32:35], v[180:183], v[196:199], v[32:35]
	v_mfma_f32_16x16x32_bf16 v[24:27], v[172:175], v[204:207], v[24:27]
	v_mfma_f32_16x16x32_bf16 v[16:19], v[180:183], v[204:207], v[16:19]
	v_mfma_f32_16x16x32_bf16 v[8:11], v[172:175], v[212:215], v[8:11]
	v_mfma_f32_16x16x32_bf16 v[0:3], v[180:183], v[212:215], v[0:3]
	s_barrier
	s_setprio 0
	s_add_u32 s28, s28, 0x100
	s_addc_u32 s29, s29, 0
	s_add_u32 s52, s52, 0x100
	s_addc_u32 s75, s75, 0
	s_cmp_ge_u32 s76, s54
	s_mov_b32 s30, s76
	s_cbranch_scc0 .LBB0_2452
	s_and_b64 vcc, exec, s[12:13]
	s_cbranch_vccz .LBB0_2455

; __global__ void __launch_bounds__(NTHREADS, 2) fwd_kernel(Args args) {
	.amdhsa_kernel _Z10fwd_kernel4Args
		.amdhsa_group_segment_fixed_size 0
		.amdhsa_private_segment_fixed_size 0
		.amdhsa_kernarg_size 464
		.amdhsa_user_sgpr_count 2
		.amdhsa_user_sgpr_dispatch_ptr 0
		.amdhsa_user_sgpr_queue_ptr 0
		.amdhsa_user_sgpr_kernarg_segment_ptr 1
		.amdhsa_user_sgpr_dispatch_id 0
		.amdhsa_user_sgpr_kernarg_preload_length 0
		.amdhsa_user_sgpr_kernarg_preload_offset 0
		.amdhsa_user_sgpr_private_segment_size 0
		.amdhsa_uses_dynamic_stack 0
		.amdhsa_enable_private_segment 0
		.amdhsa_system_sgpr_workgroup_id_x 1
		.amdhsa_system_sgpr_workgroup_id_y 0
		.amdhsa_system_sgpr_workgroup_id_z 0
		.amdhsa_system_sgpr_workgroup_info 0
		.amdhsa_system_vgpr_workitem_id 0
		.amdhsa_next_free_vgpr 256
		.amdhsa_next_free_sgpr 102
		.amdhsa_accum_offset 256
		.amdhsa_reserve_vcc 1
		.amdhsa_float_round_mode_32 0
		.amdhsa_float_round_mode_16_64 0
		.amdhsa_float_denorm_mode_32 3
		.amdhsa_float_denorm_mode_16_64 3
		.amdhsa_dx10_clamp 1
		.amdhsa_ieee_mode 1
		.amdhsa_fp16_overflow 0
		.amdhsa_tg_split 0
		.amdhsa_exception_fp_ieee_invalid_op 0
		.amdhsa_exception_fp_denorm_src 0
		.amdhsa_exception_fp_ieee_div_zero 0
		.amdhsa_exception_fp_ieee_overflow 0
		.amdhsa_exception_fp_ieee_underflow 0
		.amdhsa_exception_fp_ieee_inexact 0
		.amdhsa_exception_int_div_zero 0
	.end_amdhsa_kernel

; __global__ void __launch_bounds__(NTHREADS, 2) fwd_kernel(Args args) {
amdhsa.kernels:
  - .agpr_count:     0
    .args:
      - .offset:         0
        .size:           208
        .value_kind:     by_value
      - .offset:         208
        .size:           4
        .value_kind:     hidden_block_count_x
      - .offset:         212
        .size:           4
        .value_kind:     hidden_block_count_y
      - .offset:         216
        .size:           4
        .value_kind:     hidden_block_count_z
      - .offset:         220
        .size:           2
        .value_kind:     hidden_group_size_x
      - .offset:         222
        .size:           2
        .value_kind:     hidden_group_size_y
      - .offset:         224
        .size:           2
        .value_kind:     hidden_group_size_z
      - .offset:         226
        .size:           2
        .value_kind:     hidden_remainder_x
      - .offset:         228
        .size:           2
        .value_kind:     hidden_remainder_y
      - .offset:         230
        .size:           2
        .value_kind:     hidden_remainder_z
      - .offset:         248
        .size:           8
        .value_kind:     hidden_global_offset_x
      - .offset:         256
        .size:           8
        .value_kind:     hidden_global_offset_y
      - .offset:         264
        .size:           8
        .value_kind:     hidden_global_offset_z
      - .offset:         272
        .size:           2
        .value_kind:     hidden_grid_dims
      - .offset:         328
        .size:           4
        .value_kind:     hidden_dynamic_lds_size
    .group_segment_fixed_size: 0
    .kernarg_segment_align: 8
    .kernarg_segment_size: 464
    .language:       OpenCL C
    .language_version:
      - 2
      - 0
    .max_flat_workgroup_size: 512
    .name:           _Z10fwd_kernel4Args
    .private_segment_fixed_size: 0
    .sgpr_count:     108
    .sgpr_spill_count: 25
    .symbol:         _Z10fwd_kernel4Args.kd
    .uniform_work_group_size: 1
    .uses_dynamic_stack: false
    .vgpr_count:     256
    .vgpr_spill_count: 0
    .wavefront_size: 64
